# attention key loop: both V fragments of each PV block read ahead into spare quads (no re-read + wait of v[80:83])
# baseline (speedup 1.0000x reference)
; #define MFMA(a, b, c) __builtin_amdgcn_mfma_f32_32x32x16_bf16((a), (b), (c), 0, 0, 0)
; DI unsigned pk_bf16(float lo, float hi) { f32x2v v = {lo, hi}; bf16x2v b = __builtin_convertvector(v, bf16x2v); return __builtin_bit_cast(unsigned, b); }
; #define SB_ __builtin_amdgcn_sched_barrier(0)
; DI void attn_item64(const Params& p, int it, char* smem) {
;     ...
;       { const bf16x8 kf = *(const bf16x8*)(kpe); sa = MFMA(kf, qfa[0], sinit); sb = MFMA(kf, qfb[0], sinit); }
; #pragma unroll
;       for (int c = 1; c < 6; ++c) { const bf16x8 kf = *(const bf16x8*)(((c & 1) ? kpo : kpe) + c * 32); sa = MFMA(kf, qfa[c], sa); sb = MFMA(kf, qfb[c], sb); }
;       SB_;
;       float lsa = 0.f, lsb = 0.f;
; #pragma unroll
;       for (int i = 0; i < 16; ++i) { const float e = __builtin_amdgcn_exp2f(sa[i]); sa[i] = e; lsa += e; const float f = __builtin_amdgcn_exp2f(sb[i]); sb[i] = f; lsb += f; }
;       la += lsa; lb += lsb;
;       SB_;
; #pragma unroll
;       for (int s2 = 0; s2 < 2; ++s2) {
;         uint4 pu, pv;
;         pu.x = pk_bf16(sa[8 * s2 + 0], sa[8 * s2 + 1]); pu.y = pk_bf16(sa[8 * s2 + 2], sa[8 * s2 + 3]); pu.z = pk_bf16(sa[8 * s2 + 4], sa[8 * s2 + 5]); pu.w = pk_bf16(sa[8 * s2 + 6], sa[8 * s2 + 7]);
;         pv.x = pk_bf16(sb[8 * s2 + 0], sb[8 * s2 + 1]); pv.y = pk_bf16(sb[8 * s2 + 2], sb[8 * s2 + 3]); pv.z = pk_bf16(sb[8 * s2 + 4], sb[8 * s2 + 5]); pv.w = pk_bf16(sb[8 * s2 + 6], sb[8 * s2 + 7]);
;         const bf16x8 pa_ = __builtin_bit_cast(bf16x8, pu), pb_ = __builtin_bit_cast(bf16x8, pv);
; #pragma unroll
;         for (int vt = 0; vt < 2; ++vt) {
;           const char* vp = cur + KBYTES + (vt * 32 + r) * VROW + (t2 * 32 + 16 * s2 + 4 * hh) * 2;
;           const uint2 lo = *(const uint2*)(vp), hi = *(const uint2*)(vp + 16);
;           uint4 vu; vu.x = lo.x; vu.y = lo.y; vu.z = hi.x; vu.w = hi.y;
;           const bf16x8 vf = __builtin_bit_cast(bf16x8, vu);
;           oa[vt] = MFMA(vf, pa_, oa[vt]);
;           ob[vt] = MFMA(vf, pb_, ob[vt]);
;         }
;       }
.LBB0_548:
	s_or_b64 exec, exec, s[4:5]
	global_load_dwordx4 v[160:163], v[170:171], off
	s_cmp_eq_u32 s7, 1
	s_cselect_b32 s4, 0, 0x5200
	v_or_b32_e32 v80, s4, v211
	v_add_u32_e32 v80, v80, v210
	v_or_b32_e32 v81, s4, v164
	v_add_u32_e32 v168, v80, v212
	v_add3_u32 v213, v80, v207, v206
	v_add_u32_e32 v80, s6, v209
	v_add_u32_e32 v188, v168, v206
	v_add_u32_e32 v195, v81, v208
	v_add_u32_e32 v238, 0x3000, v80
	ds_read_b128 v[176:179], v168
	ds_read_b128 v[242:245], v188 offset:32
	ds_read_b128 v[180:183], v168 offset:64
	ds_read_b128 v[246:249], v188 offset:96
	ds_read_b128 v[184:187], v168 offset:128
	s_waitcnt lgkmcnt(4)
	v_mfma_f32_32x32x16_bf16 v[80:95], v[176:179], v[152:155], v[64:79]
	v_mfma_f32_32x32x16_bf16 v[96:111], v[176:179], v[156:159], v[64:79]
	ds_read_b128 v[176:179], v188 offset:160
	s_waitcnt lgkmcnt(4)
	v_mfma_f32_32x32x16_bf16 v[80:95], v[242:245], v[136:139], v[80:95]
	v_mfma_f32_32x32x16_bf16 v[96:111], v[242:245], v[140:143], v[96:111]
	s_waitcnt lgkmcnt(3)
	v_mfma_f32_32x32x16_bf16 v[80:95], v[180:183], v[144:147], v[80:95]
	v_mfma_f32_32x32x16_bf16 v[96:111], v[180:183], v[148:151], v[96:111]
	s_waitcnt lgkmcnt(2)
	v_mfma_f32_32x32x16_bf16 v[80:95], v[246:249], v[112:115], v[80:95]
	v_mfma_f32_32x32x16_bf16 v[96:111], v[246:249], v[124:127], v[96:111]
	s_waitcnt lgkmcnt(1)
	v_mfma_f32_32x32x16_bf16 v[80:95], v[184:187], v[128:131], v[80:95]
	v_mfma_f32_32x32x16_bf16 v[96:111], v[184:187], v[132:135], v[96:111]
	s_waitcnt lgkmcnt(0)
	v_mfma_f32_32x32x16_bf16 v[80:95], v[176:179], v[116:119], v[80:95]
	v_mfma_f32_32x32x16_bf16 v[96:111], v[176:179], v[120:123], v[96:111]
	v_add_u32_e32 v239, 0x3000, v195
	v_add_u32_e32 v240, 0x4000, v195
	ds_read2_b64 v[242:245], v239 offset1:2
	ds_read2_b64 v[246:249], v240 offset0:32 offset1:34
	s_nop 10
	v_exp_f32_e32 v214, v80
	v_exp_f32_e32 v215, v81
	v_exp_f32_e32 v216, v82
	v_exp_f32_e32 v217, v83
	v_add_f32_e32 v80, 0, v214
	v_exp_f32_e32 v218, v84
	v_add_f32_e32 v80, v215, v80
	v_exp_f32_e32 v219, v85
	v_add_f32_e32 v80, v216, v80
	v_exp_f32_e32 v222, v86
	v_add_f32_e32 v80, v217, v80
	v_add_f32_e32 v80, v218, v80
	v_add_f32_e32 v80, v219, v80
	v_exp_f32_e32 v96, v96
	v_exp_f32_e32 v97, v97
	v_exp_f32_e32 v98, v98
	v_exp_f32_e32 v99, v99
	v_exp_f32_e32 v100, v100
	v_exp_f32_e32 v101, v101
	v_exp_f32_e32 v102, v102
	v_exp_f32_e32 v188, v87
	v_exp_f32_e32 v189, v103
	v_exp_f32_e32 v186, v88
	v_exp_f32_e32 v187, v104
	v_exp_f32_e32 v190, v89
	v_exp_f32_e32 v191, v105
	v_exp_f32_e32 v192, v90
	v_exp_f32_e32 v193, v106
	v_exp_f32_e32 v180, v91
	v_exp_f32_e32 v181, v107
	v_exp_f32_e32 v182, v92
	v_exp_f32_e32 v183, v108
	v_exp_f32_e32 v184, v93
	v_exp_f32_e32 v185, v109
	v_exp_f32_e32 v176, v94
	v_exp_f32_e32 v177, v110
	v_exp_f32_e32 v178, v95
	v_exp_f32_e32 v179, v111
	v_add_f32_e32 v194, v222, v80
	v_cvt_pk_bf16_f32 v84, v214, v215
	v_cvt_pk_bf16_f32 v85, v216, v217
	v_cvt_pk_bf16_f32 v86, v218, v219
	v_cvt_pk_bf16_f32 v87, v222, v188
	v_cvt_pk_bf16_f32 v88, v96, v97
	v_cvt_pk_bf16_f32 v89, v98, v99
	v_cvt_pk_bf16_f32 v90, v100, v101
	v_cvt_pk_bf16_f32 v91, v102, v189
	s_waitcnt lgkmcnt(0)
	v_mfma_f32_32x32x16_bf16 v[48:63], v[242:245], v[84:87], v[48:63]
	v_mfma_f32_32x32x16_bf16 v[32:47], v[242:245], v[88:91], v[32:47]
	ds_read2_b64 v[214:217], v239 offset0:4 offset1:6
	ds_read2_b64 v[222:225], v240 offset0:36 offset1:38
	s_waitcnt lgkmcnt(2)
	v_mfma_f32_32x32x16_bf16 v[16:31], v[246:249], v[84:87], v[16:31]
	v_add_f32_e32 v84, 0, v96
	v_add_f32_e32 v84, v97, v84
	v_add_f32_e32 v84, v98, v84
	v_add_f32_e32 v84, v99, v84
	v_add_f32_e32 v84, v100, v84
	v_add_f32_e32 v84, v101, v84
	v_add_f32_e32 v195, v102, v84
	v_mfma_f32_32x32x16_bf16 v[0:15], v[246:249], v[88:91], v[0:15]
	ds_read_b128 v[226:229], v168 offset:6144
	ds_read_b128 v[242:245], v213 offset:32
	ds_read_b128 v[230:233], v168 offset:6208
	ds_read_b128 v[246:249], v213 offset:96
	ds_read_b128 v[234:237], v168 offset:6272
	s_waitcnt lgkmcnt(4)
	v_mfma_f32_32x32x16_bf16 v[80:95], v[226:229], v[152:155], v[64:79]
	v_mfma_f32_32x32x16_bf16 v[96:111], v[226:229], v[156:159], v[64:79]
	ds_read_b128 v[226:229], v213 offset:160
	s_waitcnt lgkmcnt(4)
	v_mfma_f32_32x32x16_bf16 v[80:95], v[242:245], v[136:139], v[80:95]
	v_mfma_f32_32x32x16_bf16 v[96:111], v[242:245], v[140:143], v[96:111]
	s_waitcnt lgkmcnt(3)
	v_mfma_f32_32x32x16_bf16 v[80:95], v[230:233], v[144:147], v[80:95]
	v_mfma_f32_32x32x16_bf16 v[96:111], v[230:233], v[148:151], v[96:111]
	s_waitcnt lgkmcnt(2)
	v_mfma_f32_32x32x16_bf16 v[80:95], v[246:249], v[112:115], v[80:95]
	v_mfma_f32_32x32x16_bf16 v[96:111], v[246:249], v[124:127], v[96:111]
	s_waitcnt lgkmcnt(1)
	v_mfma_f32_32x32x16_bf16 v[80:95], v[234:237], v[128:131], v[80:95]
	v_mfma_f32_32x32x16_bf16 v[96:111], v[234:237], v[132:135], v[96:111]
	s_waitcnt lgkmcnt(0)
; #define MFMA(a, b, c) __builtin_amdgcn_mfma_f32_32x32x16_bf16((a), (b), (c), 0, 0, 0)
; DI unsigned pk_bf16(float lo, float hi) { f32x2v v = {lo, hi}; bf16x2v b = __builtin_convertvector(v, bf16x2v); return __builtin_bit_cast(unsigned, b); }
; #define SB_ __builtin_amdgcn_sched_barrier(0)
; #define ATT64_STORE(base) do { \
;     { uint2* d = (uint2*)((base) + vlo0); d[0] = make_uint2(rv0.x, rv0.y); d[1] = make_uint2(rv0.z, rv0.w); } } while (0)
; DI void attn_item64(const Params& p, int it, char* smem) {
;     ...
;       { const bf16x8 kf = *(const bf16x8*)(kpe); sa = MFMA(kf, qfa[0], sinit); sb = MFMA(kf, qfb[0], sinit); }
; #pragma unroll
;       for (int c = 1; c < 6; ++c) { const bf16x8 kf = *(const bf16x8*)(((c & 1) ? kpo : kpe) + c * 32); sa = MFMA(kf, qfa[c], sa); sb = MFMA(kf, qfb[c], sb); }
;       SB_;
;       float lsa = 0.f, lsb = 0.f;
; #pragma unroll
;       for (int i = 0; i < 16; ++i) { const float e = __builtin_amdgcn_exp2f(sa[i]); sa[i] = e; lsa += e; const float f = __builtin_amdgcn_exp2f(sb[i]); sb[i] = f; lsb += f; }
;       la += lsa; lb += lsb;
;       SB_;
; #pragma unroll
;       for (int s2 = 0; s2 < 2; ++s2) {
;         uint4 pu, pv;
;         pu.x = pk_bf16(sa[8 * s2 + 0], sa[8 * s2 + 1]); pu.y = pk_bf16(sa[8 * s2 + 2], sa[8 * s2 + 3]); pu.z = pk_bf16(sa[8 * s2 + 4], sa[8 * s2 + 5]); pu.w = pk_bf16(sa[8 * s2 + 6], sa[8 * s2 + 7]);
;         pv.x = pk_bf16(sb[8 * s2 + 0], sb[8 * s2 + 1]); pv.y = pk_bf16(sb[8 * s2 + 2], sb[8 * s2 + 3]); pv.z = pk_bf16(sb[8 * s2 + 4], sb[8 * s2 + 5]); pv.w = pk_bf16(sb[8 * s2 + 6], sb[8 * s2 + 7]);
;         const bf16x8 pa_ = __builtin_bit_cast(bf16x8, pu), pb_ = __builtin_bit_cast(bf16x8, pv);
; #pragma unroll
;         for (int vt = 0; vt < 2; ++vt) {
;           const char* vp = cur + KBYTES + (vt * 32 + r) * VROW + (t2 * 32 + 16 * s2 + 4 * hh) * 2;
;           const uint2 lo = *(const uint2*)(vp), hi = *(const uint2*)(vp + 16);
;           uint4 vu; vu.x = lo.x; vu.y = lo.y; vu.z = hi.x; vu.w = hi.y;
;           const bf16x8 vf = __builtin_bit_cast(bf16x8, vu);
;           oa[vt] = MFMA(vf, pa_, oa[vt]);
;           ob[vt] = MFMA(vf, pb_, ob[vt]);
;         }
;       }
;       SB_;
;     }
;     SB_;
;     if (more) { char* nxt = smem + ((kt + 1) & 1) * STAGE; ATT64_STORE(nxt); }
;     __syncthreads();
	v_mfma_f32_32x32x16_bf16 v[80:95], v[226:229], v[116:119], v[80:95]
	v_mfma_f32_32x32x16_bf16 v[96:111], v[226:229], v[120:123], v[96:111]
	s_nop 10
	v_exp_f32_e32 v168, v80
	v_exp_f32_e32 v213, v81
	v_exp_f32_e32 v233, v96
	v_exp_f32_e32 v96, v82
	v_exp_f32_e32 v234, v97
	v_exp_f32_e32 v97, v83
	v_add_f32_e32 v80, 0, v168
	v_exp_f32_e32 v235, v98
	v_exp_f32_e32 v98, v84
	v_add_f32_e32 v80, v213, v80
	v_exp_f32_e32 v236, v99
	v_exp_f32_e32 v99, v85
	v_add_f32_e32 v80, v96, v80
	v_add_f32_e32 v80, v97, v80
	v_add_f32_e32 v80, v98, v80
	v_exp_f32_e32 v237, v100
	v_exp_f32_e32 v241, v101
	v_exp_f32_e32 v100, v86
	v_exp_f32_e32 v101, v102
	v_exp_f32_e32 v102, v87
	v_exp_f32_e32 v103, v103
	v_exp_f32_e32 v218, v88
	v_exp_f32_e32 v219, v104
	v_exp_f32_e32 v104, v89
	v_exp_f32_e32 v105, v105
	v_exp_f32_e32 v226, v90
	v_exp_f32_e32 v227, v106
	v_exp_f32_e32 v106, v91
	v_exp_f32_e32 v107, v107
	v_exp_f32_e32 v228, v92
	v_exp_f32_e32 v229, v108
	v_exp_f32_e32 v108, v93
	v_exp_f32_e32 v109, v109
	v_exp_f32_e32 v230, v94
	v_exp_f32_e32 v231, v110
	v_exp_f32_e32 v110, v95
	v_exp_f32_e32 v111, v111
	v_add_f32_e32 v232, v99, v80
	v_cvt_pk_bf16_f32 v80, v186, v190
	v_cvt_pk_bf16_f32 v81, v192, v180
	v_cvt_pk_bf16_f32 v82, v182, v184
	v_cvt_pk_bf16_f32 v83, v176, v178
	v_cvt_pk_bf16_f32 v84, v187, v191
	v_cvt_pk_bf16_f32 v85, v193, v181
	v_mfma_f32_32x32x16_bf16 v[48:63], v[214:217], v[80:83], v[48:63]
	v_cvt_pk_bf16_f32 v86, v183, v185
	v_cvt_pk_bf16_f32 v87, v177, v179
	v_cvt_pk_bf16_f32 v88, v233, v234
	v_cvt_pk_bf16_f32 v89, v235, v236
	v_cvt_pk_bf16_f32 v90, v237, v241
	v_cvt_pk_bf16_f32 v91, v101, v103
	v_mfma_f32_32x32x16_bf16 v[16:31], v[222:225], v[80:83], v[16:31]
	ds_read2_b64 v[80:83], v239 offset0:8 offset1:10
	ds_read2_b64 v[246:249], v240 offset0:40 offset1:42
	v_mfma_f32_32x32x16_bf16 v[32:47], v[214:217], v[84:87], v[32:47]
	v_mfma_f32_32x32x16_bf16 v[0:15], v[222:225], v[84:87], v[0:15]
	v_cvt_pk_bf16_f32 v84, v168, v213
	v_cvt_pk_bf16_f32 v85, v96, v97
	v_cvt_pk_bf16_f32 v86, v98, v99
	v_cvt_pk_bf16_f32 v87, v100, v102
	s_waitcnt lgkmcnt(0)
	s_nop 0
	v_mfma_f32_32x32x16_bf16 v[48:63], v[80:83], v[84:87], v[48:63]
	v_mfma_f32_32x32x16_bf16 v[32:47], v[80:83], v[88:91], v[32:47]
	ds_read2_b64 v[92:95], v239 offset0:12 offset1:14
	ds_read2_b64 v[96:99], v240 offset0:44 offset1:46
	s_waitcnt lgkmcnt(2)
	v_mfma_f32_32x32x16_bf16 v[16:31], v[246:249], v[84:87], v[16:31]
	v_add_f32_e32 v84, 0, v233
	v_add_f32_e32 v84, v234, v84
	v_add_f32_e32 v84, v235, v84
	v_add_f32_e32 v84, v236, v84
	v_add_f32_e32 v84, v237, v84
	v_add_f32_e32 v233, v241, v84
	v_pk_add_f32 v[84:85], v[188:189], v[194:195]
	v_mfma_f32_32x32x16_bf16 v[0:15], v[246:249], v[88:91], v[0:15]
	v_add_f32_e64 v80, v186, v84
	v_add_f32_e64 v81, v187, v85
	v_add_f32_e64 v90, v100, v232
	v_add_f32_e64 v91, v101, v233
	v_add_f32_e64 v80, v190, v80
	v_add_f32_e64 v81, v191, v81
	v_pk_add_f32 v[90:91], v[102:103], v[90:91]
	v_pk_add_f32 v[84:85], v[192:193], v[80:81]
	v_cvt_pk_bf16_f32 v80, v218, v104
	v_pk_add_f32 v[84:85], v[180:181], v[84:85]
	v_cvt_pk_bf16_f32 v81, v226, v106
	v_pk_add_f32 v[84:85], v[182:183], v[84:85]
	v_cvt_pk_bf16_f32 v82, v228, v108
	v_cvt_pk_bf16_f32 v83, v230, v110
	v_pk_add_f32 v[88:89], v[184:185], v[84:85]
	v_cvt_pk_bf16_f32 v84, v219, v105
	v_cvt_pk_bf16_f32 v85, v227, v107
	v_cvt_pk_bf16_f32 v86, v229, v109
	v_cvt_pk_bf16_f32 v87, v231, v111
	v_pk_add_f32 v[90:91], v[218:219], v[90:91]
	s_waitcnt lgkmcnt(1)
	v_mfma_f32_32x32x16_bf16 v[48:63], v[92:95], v[80:83], v[48:63]
	v_add_f32_e64 v90, v104, v90
	v_add_f32_e64 v91, v105, v91
	v_add_f32_e64 v88, v176, v88
	v_add_f32_e64 v89, v177, v89
	v_add_f32_e64 v88, v178, v88
	v_add_f32_e64 v89, v179, v89
	v_pk_add_f32 v[88:89], v[166:167], v[88:89]
	v_mfma_f32_32x32x16_bf16 v[32:47], v[92:95], v[84:87], v[32:47]
	s_waitcnt lgkmcnt(0)
	v_mfma_f32_32x32x16_bf16 v[16:31], v[96:99], v[80:83], v[16:31]
	v_add_f32_e64 v80, v226, v90
	v_add_f32_e64 v81, v227, v91
	v_add_f32_e64 v80, v106, v80
	v_add_f32_e64 v81, v107, v81
	v_add_f32_e64 v80, v228, v80
	v_add_f32_e64 v81, v229, v81
	v_pk_add_f32 v[80:81], v[108:109], v[80:81]
	v_mfma_f32_32x32x16_bf16 v[0:15], v[96:99], v[84:87], v[0:15]
	v_add_f32_e64 v80, v230, v80
	v_add_f32_e64 v81, v231, v81
	v_add_f32_e64 v80, v110, v80
	v_add_f32_e64 v81, v111, v81
	v_add_f32_e64 v166, v88, v80
	v_add_f32_e64 v167, v89, v81
	s_add_i32 s8, s8, 1
	v_lshl_add_u64 v[170:171], v[170:171], 0, s[30:31]
	v_lshl_add_u64 v[172:173], v[172:173], 0, s[34:35]
	s_cmp_lg_u32 s8, 36
	v_lshl_add_u64 v[174:175], v[174:175], 0, s[34:35]
	s_waitcnt vmcnt(0)
	ds_write2_b64 v238, v[160:161], v[162:163] offset1:1
	s_waitcnt lgkmcnt(0)
	s_barrier
	s_cbranch_scc0 .LBB0_551
